# fox fast path, second pass: identity moves folded into the scaling sub/fmac pair, 21 dead key-index temporaries dropped
# baseline (speedup 1.0000x reference)
; DI float shflx(float v, int m, int lane) { return __int_as_float(__builtin_amdgcn_ds_bpermute((lane ^ m) << 2, __float_as_int(v))); }
; template <int MODE>
; DI void attn_item(const u16* Qp, int ldq, const u16* Kp, int ldk, const u16* VTp, int ldv, u16* Op, int ldo,
;                   int q0, int nkt, const float* Fc, const unsigned* BM, float kmaxn, char* smem) {
;     ...
;     float mx = -1e30f;
;     if (MODE == 1) {
; #pragma unroll
;       for (int k2 = 0; k2 < 2; ++k2)
; #pragma unroll
;         for (int j = 0; j < 4; ++j) {
;           const int kl = 32 * k2 + 16 * (j >> 1) + 8 * h + 4 * (j & 1);
;           const f32x4 f4 = *(const f32x4*)(sF + kl);
; #pragma unroll
;           for (int i = 0; i < 4; ++i) {
;             float x = sc[k2][j * 4 + i] * c1 + (fcq - f4[i]);
;             if (diag && (ts + kl + i > q)) x = -1e30f;
;             sc[k2][j * 4 + i] = x;
;             mx = fmaxf(mx, x);
;           }
;         }
;     } else {
; #pragma unroll
;       for (int k2 = 0; k2 < 2; ++k2)
; #pragma unroll
;         for (int e = 0; e < 16; ++e) mx = fmaxf(mx, sc[k2][e]);
;       mx *= c1;
;     }
;     mx = fmaxf(mx, shflx(mx, 32, lane));
;     if (__any(mx > m_run + 8.f)) {
;       const float m_new = fmaxf(m_run, mx);
;       const float alpha = __builtin_amdgcn_exp2f(m_run - m_new);
;       m_run = m_new; l_run *= alpha;
; #pragma unroll
;       for (int i = 0; i < 4; ++i)
; #pragma unroll
;         for (int e = 0; e < 16; ++e) o[i][e] *= alpha;
;     }
.Lfox_fast:
	s_mov_b32 s14, 0xf149f2ca
	s_waitcnt lgkmcnt(0)
	v_sub_f32_e32 v185, v141, v166
	v_fmac_f32_e32 v185, 0x3e0293ee, v66
	v_sub_f32_e32 v191, v141, v167
	v_fmac_f32_e32 v191, 0x3e0293ee, v67
	v_sub_f32_e32 v192, v141, v168
	v_fmac_f32_e32 v192, 0x3e0293ee, v68
	v_sub_f32_e32 v193, v141, v169
	v_fmac_f32_e32 v193, 0x3e0293ee, v69
	v_sub_f32_e32 v198, v141, v172
	v_fmac_f32_e32 v198, 0x3e0293ee, v70
	v_sub_f32_e32 v197, v141, v173
	v_fmac_f32_e32 v197, 0x3e0293ee, v71
	v_sub_f32_e32 v195, v141, v174
	v_fmac_f32_e32 v195, 0x3e0293ee, v72
	v_max3_f32 v66, v185, s14, v191
	v_sub_f32_e32 v196, v141, v175
	v_max3_f32 v66, v66, v192, v193
	v_fmac_f32_e32 v196, 0x3e0293ee, v73
	v_max3_f32 v66, v66, v198, v197
	v_max3_f32 v70, v66, v195, v196
	s_waitcnt lgkmcnt(0)
	v_sub_f32_e32 v184, v141, v212
	v_fmac_f32_e32 v184, 0x3e0293ee, v74
	v_sub_f32_e32 v183, v141, v213
	v_fmac_f32_e32 v183, 0x3e0293ee, v75
	v_sub_f32_e32 v182, v141, v214
	v_fmac_f32_e32 v182, 0x3e0293ee, v76
	v_sub_f32_e32 v179, v141, v215
	v_fmac_f32_e32 v179, 0x3e0293ee, v77
	v_max3_f32 v66, v70, v184, v183
	v_max3_f32 v70, v66, v182, v179
	s_waitcnt lgkmcnt(0)
	v_sub_f32_e32 v194, v141, v234
	v_fmac_f32_e32 v194, 0x3e0293ee, v78
	v_sub_f32_e32 v188, v141, v235
	v_fmac_f32_e32 v188, 0x3e0293ee, v79
	v_sub_f32_e32 v186, v141, v236
	v_fmac_f32_e32 v186, 0x3e0293ee, v80
	v_sub_f32_e32 v187, v141, v237
	v_fmac_f32_e32 v187, 0x3e0293ee, v81
	v_max3_f32 v66, v70, v194, v188
	v_max3_f32 v70, v66, v186, v187
	s_waitcnt lgkmcnt(0)
	v_sub_f32_e32 v176, v141, v238
	v_fmac_f32_e32 v176, 0x3e0293ee, v82
	v_sub_f32_e32 v175, v141, v239
	v_fmac_f32_e32 v175, 0x3e0293ee, v83
	v_sub_f32_e32 v174, v141, v240
	v_fmac_f32_e32 v174, 0x3e0293ee, v84
	v_sub_f32_e32 v173, v141, v241
	v_fmac_f32_e32 v173, 0x3e0293ee, v85
	v_max3_f32 v66, v70, v176, v175
	v_max3_f32 v70, v66, v174, v173
	s_waitcnt lgkmcnt(0)
	v_sub_f32_e32 v190, v141, v242
	v_fmac_f32_e32 v190, 0x3e0293ee, v86
	v_sub_f32_e32 v180, v141, v243
	v_fmac_f32_e32 v180, 0x3e0293ee, v87
	v_sub_f32_e32 v177, v141, v244
	v_fmac_f32_e32 v177, 0x3e0293ee, v88
	v_sub_f32_e32 v178, v141, v245
	v_fmac_f32_e32 v178, 0x3e0293ee, v89
	v_max3_f32 v66, v70, v190, v180
	v_max3_f32 v70, v66, v177, v178
	s_waitcnt lgkmcnt(0)
	v_sub_f32_e32 v169, v141, v246
	v_fmac_f32_e32 v169, 0x3e0293ee, v90
	v_sub_f32_e32 v168, v141, v247
	v_fmac_f32_e32 v168, 0x3e0293ee, v91
	v_sub_f32_e32 v167, v141, v248
	v_fmac_f32_e32 v167, 0x3e0293ee, v92
	v_sub_f32_e32 v166, v141, v249
	v_fmac_f32_e32 v166, 0x3e0293ee, v93
	v_max3_f32 v66, v70, v169, v168
	v_max3_f32 v70, v66, v167, v166
	v_add_u32_e32 v71, -11, v171
	s_waitcnt lgkmcnt(0)
	v_sub_f32_e32 v181, v141, v250
	v_fmac_f32_e32 v181, 0x3e0293ee, v94
	v_sub_f32_e32 v172, v141, v251
	v_fmac_f32_e32 v172, 0x3e0293ee, v95
	v_sub_f32_e32 v170, v141, v252
	v_fmac_f32_e32 v170, 0x3e0293ee, v96
	v_add_u32_e32 v68, -8, v171
	v_sub_f32_e32 v171, v141, v253
	v_fmac_f32_e32 v171, 0x3e0293ee, v97
	v_max3_f32 v66, v70, v181, v172
	v_max3_f32 v66, v66, v170, v171
	ds_bpermute_b32 v67, v143, v66
	s_waitcnt lgkmcnt(0)
	v_max_f32_e32 v67, v67, v67
	v_max_f32_e32 v66, v66, v67
	v_add_f32_e32 v67, 0x41000000, v164
	v_cmp_gt_f32_e32 vcc, v66, v67
	s_cbranch_vccz .Lfox_f477
	v_max_f32_e32 v66, v66, v66
	v_max_f32_e32 v67, v164, v164
	v_max_f32_e32 v67, v67, v66
	v_sub_f32_e32 v66, v164, v67
	v_exp_f32_e32 v66, v66
	v_mov_b32_e32 v164, v67
	v_pk_mul_f32 v[64:65], v[64:65], v[66:67] op_sel_hi:[1,0]
	v_pk_mul_f32 v[62:63], v[62:63], v[66:67] op_sel_hi:[1,0]
	v_pk_mul_f32 v[60:61], v[60:61], v[66:67] op_sel_hi:[1,0]
	v_pk_mul_f32 v[58:59], v[58:59], v[66:67] op_sel_hi:[1,0]
	v_pk_mul_f32 v[56:57], v[56:57], v[66:67] op_sel_hi:[1,0]
	v_pk_mul_f32 v[54:55], v[54:55], v[66:67] op_sel_hi:[1,0]
	v_pk_mul_f32 v[52:53], v[52:53], v[66:67] op_sel_hi:[1,0]
	v_pk_mul_f32 v[50:51], v[50:51], v[66:67] op_sel_hi:[1,0]
	v_pk_mul_f32 v[48:49], v[48:49], v[66:67] op_sel_hi:[1,0]
	v_pk_mul_f32 v[46:47], v[46:47], v[66:67] op_sel_hi:[1,0]
	v_pk_mul_f32 v[44:45], v[44:45], v[66:67] op_sel_hi:[1,0]
	v_pk_mul_f32 v[42:43], v[42:43], v[66:67] op_sel_hi:[1,0]
	v_pk_mul_f32 v[40:41], v[40:41], v[66:67] op_sel_hi:[1,0]
	v_pk_mul_f32 v[38:39], v[38:39], v[66:67] op_sel_hi:[1,0]
	v_pk_mul_f32 v[36:37], v[36:37], v[66:67] op_sel_hi:[1,0]
	v_pk_mul_f32 v[34:35], v[34:35], v[66:67] op_sel_hi:[1,0]
	v_pk_mul_f32 v[32:33], v[32:33], v[66:67] op_sel_hi:[1,0]
	v_pk_mul_f32 v[30:31], v[30:31], v[66:67] op_sel_hi:[1,0]
	v_pk_mul_f32 v[28:29], v[28:29], v[66:67] op_sel_hi:[1,0]
	v_pk_mul_f32 v[26:27], v[26:27], v[66:67] op_sel_hi:[1,0]
	v_pk_mul_f32 v[24:25], v[24:25], v[66:67] op_sel_hi:[1,0]
	v_pk_mul_f32 v[22:23], v[22:23], v[66:67] op_sel_hi:[1,0]
	v_pk_mul_f32 v[20:21], v[20:21], v[66:67] op_sel_hi:[1,0]
	v_pk_mul_f32 v[18:19], v[18:19], v[66:67] op_sel_hi:[1,0]
	v_pk_mul_f32 v[16:17], v[16:17], v[66:67] op_sel_hi:[1,0]
	v_pk_mul_f32 v[14:15], v[14:15], v[66:67] op_sel_hi:[1,0]
	v_pk_mul_f32 v[12:13], v[12:13], v[66:67] op_sel_hi:[1,0]
	v_pk_mul_f32 v[10:11], v[10:11], v[66:67] op_sel_hi:[1,0]
	v_pk_mul_f32 v[8:9], v[8:9], v[66:67] op_sel_hi:[1,0]
	v_pk_mul_f32 v[6:7], v[6:7], v[66:67] op_sel_hi:[1,0]
	v_pk_mul_f32 v[4:5], v[4:5], v[66:67] op_sel_hi:[1,0]
	v_pk_mul_f32 v[2:3], v[2:3], v[66:67] op_sel_hi:[1,0]
	v_mul_f32_e32 v161, v161, v66
